# fb_prompt K-loop: global->LDS staging loads software-pipelined 2 deep through two free quads (vmcnt(1) instead of vmcnt(0) per load); size-neutral
# baseline (speedup 1.0000x reference)
.LBB0_16:
	v_ashrrev_i32_e32 v0, 3, v143
	v_lshrrev_b32_e32 v1, 29, v0
	v_add_lshl_u32 v1, v0, v1, 3
	v_and_b32_e32 v1, 0xffffffc0, v1
	v_and_b32_e32 v2, 56, v211
	v_and_b32_e32 v0, 7, v0
	v_or3_b32 v190, v1, v2, v0
	v_ashrrev_i32_e32 v191, 31, v190
	v_lshlrev_b64 v[188:189], 8, v[190:191]
	v_or_b32_e32 v0, v188, v144
	v_mov_b32_e32 v1, v189
	v_lshlrev_b64 v[0:1], 9, v[0:1]
	v_lshl_add_u64 v[198:199], v[146:147], 0, v[0:1]
	v_or_b32_e32 v0, v188, v148
	v_mov_b32_e32 v1, v189
	v_lshlrev_b64 v[0:1], 9, v[0:1]
	v_lshl_add_u64 v[196:197], v[146:147], 0, v[0:1]
	v_or_b32_e32 v0, v188, v150
	v_mov_b32_e32 v1, v189
	v_lshlrev_b64 v[0:1], 9, v[0:1]
	v_lshl_add_u64 v[194:195], v[146:147], 0, v[0:1]
	v_or_b32_e32 v0, v188, v152
	v_mov_b32_e32 v1, v189
	v_lshlrev_b64 v[0:1], 9, v[0:1]
	v_lshl_add_u64 v[192:193], v[146:147], 0, v[0:1]
	global_load_dwordx4 v[244:247], v[198:199], off
	global_load_dwordx4 v[248:251], v[196:197], off
	v_and_or_b32 v128, v188, s16, v158
	v_lshlrev_b32_e32 v128, 1, v128
	v_add_u32_e32 v143, s23, v143
	s_movk_i32 s0, 0x1ff
	v_cmp_lt_i32_e32 vcc, s0, v143
	v_add_u32_e32 v211, s20, v211
	s_or_b64 s[12:13], vcc, s[12:13]
	s_waitcnt vmcnt(1)
	ds_write_b128 v145, v[244:247]
	global_load_dwordx4 v[244:247], v[194:195], off
	s_waitcnt vmcnt(1)
	ds_write_b128 v149, v[248:251]
	global_load_dwordx4 v[248:251], v[192:193], off
	s_waitcnt vmcnt(1)
	ds_write_b128 v151, v[244:247]
	global_load_dwordx4 v[244:247], v[154:155], off
	s_waitcnt vmcnt(1)
	ds_write_b128 v153, v[248:251]
	global_load_dwordx4 v[248:251], v[156:157], off
	s_waitcnt vmcnt(1)
	ds_write_b128 v159, v[244:247]
	global_load_dwordx4 v[244:247], v[198:199], off offset:64
	s_waitcnt vmcnt(1)
	ds_write_b128 v200, v[248:251]
	s_waitcnt lgkmcnt(0)
	s_barrier
	ds_read_b128 v[0:3], v203 offset:2560
	ds_read_b128 v[4:7], v203 offset:5120
	ds_read_b128 v[8:11], v203 offset:7680
	ds_read_b128 v[12:15], v204 offset:23040
	ds_read_b128 v[16:19], v203
	ds_read_b128 v[130:133], v203 offset:32
	ds_read_b128 v[64:67], v204 offset:20480
	ds_read_b128 v[134:137], v204 offset:20512
	s_waitcnt lgkmcnt(1)
	v_mfma_f32_32x32x16_bf16 v[112:127], v[16:19], v[64:67], 0
	ds_read_b128 v[212:215], v203 offset:2592
	ds_read_b128 v[216:219], v203 offset:5152
	ds_read_b128 v[220:223], v203 offset:7712
	ds_read_b128 v[224:227], v204 offset:23072
	v_mfma_f32_32x32x16_bf16 v[48:63], v[16:19], v[12:15], 0
	s_waitcnt lgkmcnt(4)
	v_mfma_f32_32x32x16_bf16 v[112:127], v[130:133], v[134:137], v[112:127]
	s_waitcnt lgkmcnt(0)
	v_mfma_f32_32x32x16_bf16 v[48:63], v[130:133], v[224:227], v[48:63]
	global_load_dwordx4 v[248:251], v[196:197], off offset:64
	s_waitcnt vmcnt(1)
	ds_write_b128 v205, v[244:247]
	global_load_dwordx4 v[244:247], v[194:195], off offset:64
	v_mfma_f32_32x32x16_bf16 v[96:111], v[0:3], v[64:67], 0
	s_waitcnt vmcnt(1)
	ds_write_b128 v206, v[248:251]
	global_load_dwordx4 v[248:251], v[192:193], off offset:64
	v_mfma_f32_32x32x16_bf16 v[32:47], v[0:3], v[12:15], 0
	s_waitcnt vmcnt(1)
	ds_write_b128 v207, v[244:247]
	global_load_dwordx4 v[244:247], v[160:161], off
	v_mfma_f32_32x32x16_bf16 v[80:95], v[4:7], v[64:67], 0
	s_waitcnt vmcnt(1)
	ds_write_b128 v208, v[248:251]
	global_load_dwordx4 v[248:251], v[162:163], off
	v_mfma_f32_32x32x16_bf16 v[16:31], v[4:7], v[12:15], 0
	s_waitcnt vmcnt(1)
	ds_write_b128 v209, v[244:247]
	global_load_dwordx4 v[244:247], v[198:199], off offset:128
	v_mfma_f32_32x32x16_bf16 v[64:79], v[8:11], v[64:67], 0
	s_waitcnt vmcnt(1)
	ds_write_b128 v210, v[248:251]
	v_mfma_f32_32x32x16_bf16 v[0:15], v[8:11], v[12:15], 0
	s_waitcnt lgkmcnt(0)
	s_barrier
	v_mfma_f32_32x32x16_bf16 v[96:111], v[212:215], v[134:137], v[96:111]
	v_mfma_f32_32x32x16_bf16 v[32:47], v[212:215], v[224:227], v[32:47]
	v_mfma_f32_32x32x16_bf16 v[80:95], v[216:219], v[134:137], v[80:95]
	v_mfma_f32_32x32x16_bf16 v[16:31], v[216:219], v[224:227], v[16:31]
	v_mfma_f32_32x32x16_bf16 v[64:79], v[220:223], v[134:137], v[64:79]
	v_mfma_f32_32x32x16_bf16 v[0:15], v[220:223], v[224:227], v[0:15]
	ds_read_b128 v[130:133], v203 offset:33280
	ds_read_b128 v[134:137], v203 offset:35840
	ds_read_b128 v[212:215], v203 offset:38400
	ds_read_b128 v[216:219], v204 offset:53760
	ds_read_b128 v[220:223], v203 offset:30720
	ds_read_b128 v[224:227], v203 offset:30752
	ds_read_b128 v[228:231], v204 offset:51200
	ds_read_b128 v[236:239], v204 offset:51232
	s_waitcnt lgkmcnt(1)
	v_mfma_f32_32x32x16_bf16 v[96:111], v[130:133], v[228:231], v[96:111]
	v_mfma_f32_32x32x16_bf16 v[32:47], v[130:133], v[216:219], v[32:47]
	v_mfma_f32_32x32x16_bf16 v[48:63], v[220:223], v[216:219], v[48:63]
	v_mfma_f32_32x32x16_bf16 v[80:95], v[134:137], v[228:231], v[80:95]
	v_mfma_f32_32x32x16_bf16 v[16:31], v[134:137], v[216:219], v[16:31]
	v_mfma_f32_32x32x16_bf16 v[64:79], v[212:215], v[228:231], v[64:79]
	v_mfma_f32_32x32x16_bf16 v[0:15], v[212:215], v[216:219], v[0:15]
	ds_read_b128 v[130:133], v203 offset:33312
	ds_read_b128 v[134:137], v203 offset:35872
	ds_read_b128 v[212:215], v203 offset:38432
	ds_read_b128 v[216:219], v204 offset:53792
	s_waitcnt lgkmcnt(3)
	v_mfma_f32_32x32x16_bf16 v[96:111], v[130:133], v[236:239], v[96:111]
	s_waitcnt lgkmcnt(0)
	v_mfma_f32_32x32x16_bf16 v[32:47], v[130:133], v[216:219], v[32:47]
	global_load_dwordx4 v[248:251], v[196:197], off offset:128
	s_waitcnt vmcnt(1)
	ds_write_b128 v145, v[244:247]
	global_load_dwordx4 v[244:247], v[194:195], off offset:128
	v_mfma_f32_32x32x16_bf16 v[112:127], v[220:223], v[228:231], v[112:127]
	s_waitcnt vmcnt(1)
	ds_write_b128 v149, v[248:251]
	global_load_dwordx4 v[248:251], v[192:193], off offset:128
	v_mfma_f32_32x32x16_bf16 v[48:63], v[224:227], v[216:219], v[48:63]
	s_waitcnt vmcnt(1)
	ds_write_b128 v151, v[244:247]
	global_load_dwordx4 v[244:247], v[164:165], off
	v_mfma_f32_32x32x16_bf16 v[80:95], v[134:137], v[236:239], v[80:95]
	s_waitcnt vmcnt(1)
	ds_write_b128 v153, v[248:251]
	global_load_dwordx4 v[248:251], v[166:167], off
	v_mfma_f32_32x32x16_bf16 v[16:31], v[134:137], v[216:219], v[16:31]
	s_waitcnt vmcnt(1)
	ds_write_b128 v159, v[244:247]
	global_load_dwordx4 v[244:247], v[198:199], off offset:192
	v_mfma_f32_32x32x16_bf16 v[64:79], v[212:215], v[236:239], v[64:79]
	s_waitcnt vmcnt(1)
	ds_write_b128 v200, v[248:251]
	v_mfma_f32_32x32x16_bf16 v[0:15], v[212:215], v[216:219], v[0:15]
	s_waitcnt lgkmcnt(0)
	s_barrier
	v_mfma_f32_32x32x16_bf16 v[112:127], v[224:227], v[236:239], v[112:127]
	ds_read_b128 v[130:133], v203 offset:2560
	ds_read_b128 v[134:137], v203 offset:5120
	ds_read_b128 v[212:215], v203 offset:7680
	ds_read_b128 v[216:219], v204 offset:23040
	ds_read_b128 v[220:223], v203
	ds_read_b128 v[224:227], v203 offset:32
	ds_read_b128 v[228:231], v204 offset:20480
	ds_read_b128 v[236:239], v204 offset:20512
	s_waitcnt lgkmcnt(1)
	v_mfma_f32_32x32x16_bf16 v[96:111], v[130:133], v[228:231], v[96:111]
	v_mfma_f32_32x32x16_bf16 v[32:47], v[130:133], v[216:219], v[32:47]
	v_mfma_f32_32x32x16_bf16 v[48:63], v[220:223], v[216:219], v[48:63]
	v_mfma_f32_32x32x16_bf16 v[80:95], v[134:137], v[228:231], v[80:95]
	v_mfma_f32_32x32x16_bf16 v[16:31], v[134:137], v[216:219], v[16:31]
	v_mfma_f32_32x32x16_bf16 v[64:79], v[212:215], v[228:231], v[64:79]
	v_mfma_f32_32x32x16_bf16 v[0:15], v[212:215], v[216:219], v[0:15]
	ds_read_b128 v[130:133], v203 offset:2592
	ds_read_b128 v[134:137], v203 offset:5152
	ds_read_b128 v[212:215], v203 offset:7712
	ds_read_b128 v[216:219], v204 offset:23072
	s_waitcnt lgkmcnt(3)
	v_mfma_f32_32x32x16_bf16 v[96:111], v[130:133], v[236:239], v[96:111]
	s_waitcnt lgkmcnt(0)
	v_mfma_f32_32x32x16_bf16 v[32:47], v[130:133], v[216:219], v[32:47]
	global_load_dwordx4 v[248:251], v[196:197], off offset:192
	s_waitcnt vmcnt(1)
	ds_write_b128 v205, v[244:247]
	global_load_dwordx4 v[244:247], v[194:195], off offset:192
	v_mfma_f32_32x32x16_bf16 v[112:127], v[220:223], v[228:231], v[112:127]
	s_waitcnt vmcnt(1)
	ds_write_b128 v206, v[248:251]
	global_load_dwordx4 v[248:251], v[192:193], off offset:192
	v_mfma_f32_32x32x16_bf16 v[48:63], v[224:227], v[216:219], v[48:63]
	s_waitcnt vmcnt(1)
	ds_write_b128 v207, v[244:247]
	global_load_dwordx4 v[244:247], v[168:169], off
	v_mfma_f32_32x32x16_bf16 v[80:95], v[134:137], v[236:239], v[80:95]
	s_waitcnt vmcnt(1)
	ds_write_b128 v208, v[248:251]
	global_load_dwordx4 v[248:251], v[170:171], off
	v_mfma_f32_32x32x16_bf16 v[16:31], v[134:137], v[216:219], v[16:31]
	s_waitcnt vmcnt(1)
	ds_write_b128 v209, v[244:247]
	global_load_dwordx4 v[244:247], v[198:199], off offset:256
	v_mfma_f32_32x32x16_bf16 v[64:79], v[212:215], v[236:239], v[64:79]
	s_waitcnt vmcnt(1)
	ds_write_b128 v210, v[248:251]
	v_mfma_f32_32x32x16_bf16 v[0:15], v[212:215], v[216:219], v[0:15]
	s_waitcnt lgkmcnt(0)
	s_barrier
	v_mfma_f32_32x32x16_bf16 v[112:127], v[224:227], v[236:239], v[112:127]
	ds_read_b128 v[130:133], v203 offset:33280
	ds_read_b128 v[134:137], v203 offset:35840
	ds_read_b128 v[212:215], v203 offset:38400
	ds_read_b128 v[216:219], v204 offset:53760
	ds_read_b128 v[220:223], v203 offset:30720
	ds_read_b128 v[224:227], v203 offset:30752
	ds_read_b128 v[228:231], v204 offset:51200
	ds_read_b128 v[236:239], v204 offset:51232
	s_waitcnt lgkmcnt(1)
	v_mfma_f32_32x32x16_bf16 v[96:111], v[130:133], v[228:231], v[96:111]
	v_mfma_f32_32x32x16_bf16 v[32:47], v[130:133], v[216:219], v[32:47]
	v_mfma_f32_32x32x16_bf16 v[48:63], v[220:223], v[216:219], v[48:63]
	v_mfma_f32_32x32x16_bf16 v[80:95], v[134:137], v[228:231], v[80:95]
	v_mfma_f32_32x32x16_bf16 v[16:31], v[134:137], v[216:219], v[16:31]
	v_mfma_f32_32x32x16_bf16 v[64:79], v[212:215], v[228:231], v[64:79]
	v_mfma_f32_32x32x16_bf16 v[0:15], v[212:215], v[216:219], v[0:15]
	ds_read_b128 v[130:133], v203 offset:33312
	ds_read_b128 v[134:137], v203 offset:35872
	ds_read_b128 v[212:215], v203 offset:38432
	ds_read_b128 v[216:219], v204 offset:53792
	s_waitcnt lgkmcnt(3)
	v_mfma_f32_32x32x16_bf16 v[96:111], v[130:133], v[236:239], v[96:111]
	s_waitcnt lgkmcnt(0)
	v_mfma_f32_32x32x16_bf16 v[32:47], v[130:133], v[216:219], v[32:47]
	global_load_dwordx4 v[248:251], v[196:197], off offset:256
	s_waitcnt vmcnt(1)
	ds_write_b128 v145, v[244:247]
	global_load_dwordx4 v[244:247], v[194:195], off offset:256
	v_mfma_f32_32x32x16_bf16 v[112:127], v[220:223], v[228:231], v[112:127]
	s_waitcnt vmcnt(1)
	ds_write_b128 v149, v[248:251]
	global_load_dwordx4 v[248:251], v[192:193], off offset:256
	v_mfma_f32_32x32x16_bf16 v[48:63], v[224:227], v[216:219], v[48:63]
	s_waitcnt vmcnt(1)
	ds_write_b128 v151, v[244:247]
	global_load_dwordx4 v[244:247], v[172:173], off
	v_mfma_f32_32x32x16_bf16 v[80:95], v[134:137], v[236:239], v[80:95]
	s_waitcnt vmcnt(1)
	ds_write_b128 v153, v[248:251]
	global_load_dwordx4 v[248:251], v[174:175], off
	v_mfma_f32_32x32x16_bf16 v[16:31], v[134:137], v[216:219], v[16:31]
	s_waitcnt vmcnt(1)
	ds_write_b128 v159, v[244:247]
	global_load_dwordx4 v[244:247], v[198:199], off offset:320
	v_mfma_f32_32x32x16_bf16 v[64:79], v[212:215], v[236:239], v[64:79]
	s_waitcnt vmcnt(1)
	ds_write_b128 v200, v[248:251]
	v_mfma_f32_32x32x16_bf16 v[0:15], v[212:215], v[216:219], v[0:15]
	s_waitcnt lgkmcnt(0)
	s_barrier
	v_mfma_f32_32x32x16_bf16 v[112:127], v[224:227], v[236:239], v[112:127]
	ds_read_b128 v[130:133], v203 offset:2560
	ds_read_b128 v[134:137], v203 offset:5120
	ds_read_b128 v[212:215], v203 offset:7680
	ds_read_b128 v[216:219], v204 offset:23040
	ds_read_b128 v[220:223], v203
	ds_read_b128 v[224:227], v203 offset:32
	ds_read_b128 v[228:231], v204 offset:20480
	ds_read_b128 v[236:239], v204 offset:20512
	s_waitcnt lgkmcnt(1)
	v_mfma_f32_32x32x16_bf16 v[96:111], v[130:133], v[228:231], v[96:111]
	v_mfma_f32_32x32x16_bf16 v[32:47], v[130:133], v[216:219], v[32:47]
	v_mfma_f32_32x32x16_bf16 v[48:63], v[220:223], v[216:219], v[48:63]
	v_mfma_f32_32x32x16_bf16 v[80:95], v[134:137], v[228:231], v[80:95]
	v_mfma_f32_32x32x16_bf16 v[16:31], v[134:137], v[216:219], v[16:31]
	v_mfma_f32_32x32x16_bf16 v[64:79], v[212:215], v[228:231], v[64:79]
	v_mfma_f32_32x32x16_bf16 v[0:15], v[212:215], v[216:219], v[0:15]
	ds_read_b128 v[130:133], v203 offset:2592
	ds_read_b128 v[134:137], v203 offset:5152
	ds_read_b128 v[212:215], v203 offset:7712
	ds_read_b128 v[216:219], v204 offset:23072
	s_waitcnt lgkmcnt(3)
	v_mfma_f32_32x32x16_bf16 v[96:111], v[130:133], v[236:239], v[96:111]
	s_waitcnt lgkmcnt(0)
	v_mfma_f32_32x32x16_bf16 v[32:47], v[130:133], v[216:219], v[32:47]
	global_load_dwordx4 v[248:251], v[196:197], off offset:320
	s_waitcnt vmcnt(1)
	ds_write_b128 v205, v[244:247]
	global_load_dwordx4 v[244:247], v[194:195], off offset:320
	v_mfma_f32_32x32x16_bf16 v[112:127], v[220:223], v[228:231], v[112:127]
	s_waitcnt vmcnt(1)
	ds_write_b128 v206, v[248:251]
	global_load_dwordx4 v[248:251], v[192:193], off offset:320
	v_mfma_f32_32x32x16_bf16 v[48:63], v[224:227], v[216:219], v[48:63]
	s_waitcnt vmcnt(1)
	ds_write_b128 v207, v[244:247]
	global_load_dwordx4 v[244:247], v[176:177], off
	v_mfma_f32_32x32x16_bf16 v[80:95], v[134:137], v[236:239], v[80:95]
	s_waitcnt vmcnt(1)
	ds_write_b128 v208, v[248:251]
	global_load_dwordx4 v[248:251], v[178:179], off
	v_mfma_f32_32x32x16_bf16 v[16:31], v[134:137], v[216:219], v[16:31]
	s_waitcnt vmcnt(1)
	ds_write_b128 v209, v[244:247]
	global_load_dwordx4 v[244:247], v[198:199], off offset:384
	v_mfma_f32_32x32x16_bf16 v[64:79], v[212:215], v[236:239], v[64:79]
	s_waitcnt vmcnt(1)
	ds_write_b128 v210, v[248:251]
	v_mfma_f32_32x32x16_bf16 v[0:15], v[212:215], v[216:219], v[0:15]
	s_waitcnt lgkmcnt(0)
	s_barrier
	v_mfma_f32_32x32x16_bf16 v[112:127], v[224:227], v[236:239], v[112:127]
	ds_read_b128 v[130:133], v203 offset:33280
	ds_read_b128 v[134:137], v203 offset:35840
	ds_read_b128 v[212:215], v203 offset:38400
	ds_read_b128 v[216:219], v204 offset:53760
	ds_read_b128 v[220:223], v203 offset:30720
	ds_read_b128 v[224:227], v203 offset:30752
	ds_read_b128 v[228:231], v204 offset:51200
	ds_read_b128 v[236:239], v204 offset:51232
	s_waitcnt lgkmcnt(1)
	v_mfma_f32_32x32x16_bf16 v[96:111], v[130:133], v[228:231], v[96:111]
	v_mfma_f32_32x32x16_bf16 v[32:47], v[130:133], v[216:219], v[32:47]
	v_mfma_f32_32x32x16_bf16 v[48:63], v[220:223], v[216:219], v[48:63]
	v_mfma_f32_32x32x16_bf16 v[80:95], v[134:137], v[228:231], v[80:95]
	v_mfma_f32_32x32x16_bf16 v[16:31], v[134:137], v[216:219], v[16:31]
	v_mfma_f32_32x32x16_bf16 v[64:79], v[212:215], v[228:231], v[64:79]
	v_mfma_f32_32x32x16_bf16 v[0:15], v[212:215], v[216:219], v[0:15]
	ds_read_b128 v[130:133], v203 offset:33312
	ds_read_b128 v[134:137], v203 offset:35872
	ds_read_b128 v[212:215], v203 offset:38432
	ds_read_b128 v[216:219], v204 offset:53792
	s_waitcnt lgkmcnt(3)
	v_mfma_f32_32x32x16_bf16 v[96:111], v[130:133], v[236:239], v[96:111]
	s_waitcnt lgkmcnt(0)
	v_mfma_f32_32x32x16_bf16 v[32:47], v[130:133], v[216:219], v[32:47]
	global_load_dwordx4 v[248:251], v[196:197], off offset:384
	s_waitcnt vmcnt(1)
	ds_write_b128 v145, v[244:247]
	global_load_dwordx4 v[244:247], v[194:195], off offset:384
	v_mfma_f32_32x32x16_bf16 v[112:127], v[220:223], v[228:231], v[112:127]
	s_waitcnt vmcnt(1)
	ds_write_b128 v149, v[248:251]
	global_load_dwordx4 v[248:251], v[192:193], off offset:384
	v_mfma_f32_32x32x16_bf16 v[48:63], v[224:227], v[216:219], v[48:63]
	s_waitcnt vmcnt(1)
	ds_write_b128 v151, v[244:247]
	global_load_dwordx4 v[244:247], v[180:181], off
	v_mfma_f32_32x32x16_bf16 v[80:95], v[134:137], v[236:239], v[80:95]
	s_waitcnt vmcnt(1)
	ds_write_b128 v153, v[248:251]
	global_load_dwordx4 v[248:251], v[182:183], off
	v_mfma_f32_32x32x16_bf16 v[16:31], v[134:137], v[216:219], v[16:31]
	s_waitcnt vmcnt(1)
	ds_write_b128 v159, v[244:247]
	global_load_dwordx4 v[244:247], v[198:199], off offset:448
	v_mfma_f32_32x32x16_bf16 v[64:79], v[212:215], v[236:239], v[64:79]
	s_waitcnt vmcnt(1)
	ds_write_b128 v200, v[248:251]
	v_mfma_f32_32x32x16_bf16 v[0:15], v[212:215], v[216:219], v[0:15]
	s_waitcnt lgkmcnt(0)
	s_barrier
	v_mfma_f32_32x32x16_bf16 v[112:127], v[224:227], v[236:239], v[112:127]
	ds_read_b128 v[130:133], v203 offset:2560
	ds_read_b128 v[134:137], v203 offset:5120
	ds_read_b128 v[212:215], v203 offset:7680
	ds_read_b128 v[216:219], v204 offset:23040
	ds_read_b128 v[220:223], v203
	ds_read_b128 v[224:227], v203 offset:32
	ds_read_b128 v[228:231], v204 offset:20480
	ds_read_b128 v[236:239], v204 offset:20512
	s_waitcnt lgkmcnt(1)
	v_mfma_f32_32x32x16_bf16 v[96:111], v[130:133], v[228:231], v[96:111]
	v_mfma_f32_32x32x16_bf16 v[32:47], v[130:133], v[216:219], v[32:47]
	v_mfma_f32_32x32x16_bf16 v[48:63], v[220:223], v[216:219], v[48:63]
	v_mfma_f32_32x32x16_bf16 v[80:95], v[134:137], v[228:231], v[80:95]
	v_mfma_f32_32x32x16_bf16 v[16:31], v[134:137], v[216:219], v[16:31]
	v_mfma_f32_32x32x16_bf16 v[64:79], v[212:215], v[228:231], v[64:79]
	v_mfma_f32_32x32x16_bf16 v[0:15], v[212:215], v[216:219], v[0:15]
	ds_read_b128 v[130:133], v203 offset:2592
	ds_read_b128 v[134:137], v203 offset:5152
	ds_read_b128 v[212:215], v203 offset:7712
	ds_read_b128 v[216:219], v204 offset:23072
	s_waitcnt lgkmcnt(3)
	v_mfma_f32_32x32x16_bf16 v[96:111], v[130:133], v[236:239], v[96:111]
	s_waitcnt lgkmcnt(0)
	v_mfma_f32_32x32x16_bf16 v[32:47], v[130:133], v[216:219], v[32:47]
	global_load_dwordx4 v[248:251], v[196:197], off offset:448
	s_waitcnt vmcnt(1)
	ds_write_b128 v205, v[244:247]
	global_load_dwordx4 v[244:247], v[194:195], off offset:448
	v_mfma_f32_32x32x16_bf16 v[112:127], v[220:223], v[228:231], v[112:127]
	s_waitcnt vmcnt(1)
	ds_write_b128 v206, v[248:251]
	global_load_dwordx4 v[248:251], v[192:193], off offset:448
	v_mfma_f32_32x32x16_bf16 v[112:127], v[224:227], v[236:239], v[112:127]
	s_waitcnt vmcnt(1)
	ds_write_b128 v207, v[244:247]
	global_load_dwordx4 v[244:247], v[184:185], off
	v_mfma_f32_32x32x16_bf16 v[64:79], v[212:215], v[236:239], v[64:79]
	s_waitcnt vmcnt(1)
	ds_write_b128 v208, v[248:251]
	global_load_dwordx4 v[248:251], v[186:187], off
	v_mfma_f32_32x32x16_bf16 v[48:63], v[224:227], v[216:219], v[48:63]
	s_waitcnt vmcnt(1)
	ds_write_b128 v209, v[244:247]
	v_mfma_f32_32x32x16_bf16 v[80:95], v[134:137], v[236:239], v[80:95]
	s_waitcnt vmcnt(0)
	ds_write_b128 v210, v[248:251]
	v_mfma_f32_32x32x16_bf16 v[16:31], v[134:137], v[216:219], v[16:31]
	s_waitcnt lgkmcnt(0)
	s_barrier
	v_mfma_f32_32x32x16_bf16 v[0:15], v[212:215], v[216:219], v[0:15]
	ds_read_b128 v[130:133], v203 offset:33280
	ds_read_b128 v[134:137], v203 offset:35840
	ds_read_b128 v[192:195], v203 offset:38400
	ds_read_b128 v[196:199], v204 offset:53760
	ds_read_b128 v[212:215], v203 offset:30720
	ds_read_b128 v[216:219], v203 offset:30752
	ds_read_b128 v[220:223], v204 offset:51200
	ds_read_b128 v[224:227], v204 offset:51232
	s_waitcnt lgkmcnt(1)
	v_mfma_f32_32x32x16_bf16 v[112:127], v[212:215], v[220:223], v[112:127]
	v_mfma_f32_32x32x16_bf16 v[64:79], v[192:195], v[220:223], v[64:79]
	v_mfma_f32_32x32x16_bf16 v[96:111], v[130:133], v[220:223], v[96:111]
	v_mfma_f32_32x32x16_bf16 v[32:47], v[130:133], v[196:199], v[32:47]
	v_mfma_f32_32x32x16_bf16 v[48:63], v[212:215], v[196:199], v[48:63]
	v_mfma_f32_32x32x16_bf16 v[80:95], v[134:137], v[220:223], v[80:95]
	v_mfma_f32_32x32x16_bf16 v[16:31], v[134:137], v[196:199], v[16:31]
	v_mfma_f32_32x32x16_bf16 v[0:15], v[192:195], v[196:199], v[0:15]
	ds_read_b128 v[130:133], v203 offset:33312
	ds_read_b128 v[134:137], v203 offset:35872
	ds_read_b128 v[192:195], v203 offset:38432
	ds_read_b128 v[196:199], v204 offset:53792
	s_waitcnt lgkmcnt(0)
	s_barrier
	v_mfma_f32_32x32x16_bf16 v[112:127], v[216:219], v[224:227], v[112:127]
	v_mfma_f32_32x32x16_bf16 v[64:79], v[192:195], v[224:227], v[64:79]
	v_mfma_f32_32x32x16_bf16 v[96:111], v[130:133], v[224:227], v[96:111]
	v_mfma_f32_32x32x16_bf16 v[32:47], v[130:133], v[196:199], v[32:47]
	v_mfma_f32_32x32x16_bf16 v[80:95], v[134:137], v[224:227], v[80:95]
	v_mfma_f32_32x32x16_bf16 v[48:63], v[216:219], v[196:199], v[48:63]
	v_mfma_f32_32x32x16_bf16 v[16:31], v[134:137], v[196:199], v[16:31]
	v_mfma_f32_32x32x16_bf16 v[0:15], v[192:195], v[196:199], v[0:15]
	s_branch .Lfbp_addr
	s_nop 0
	s_nop 0
	s_nop 0
	s_nop 0
	s_nop 0
	s_nop 0
	s_nop 0
	s_nop 0
	s_nop 0
	s_nop 0
	s_nop 0
	s_nop 0
	s_nop 0
	s_nop 0
	s_nop 0
	s_nop 0
	s_nop 0
	s_nop 0
